# diff unit prologue: q-norm cross-lane reduction by permlane32/16 swap + DPP max instead of six ds_bpermute round trips
# baseline (speedup 1.0000x reference)
; __device__ __forceinline__ float sx(float v, int mask, int lane) { return __int_as_float(__builtin_amdgcn_ds_bpermute((lane ^ mask) << 2, __float_as_int(v))); }
; __device__ __forceinline__ float bf2f(unsigned short u) { return __uint_as_float((unsigned)u << 16); }
; __device__ __forceinline__ void diff_unit(const PolDiff& P, LAS unsigned char* lds, const Ptrs& X) {
;     ...
;     { float q2 = 0.f;
; #pragma unroll
;       for (int d0 = 0; d0 < 4; ++d0)
; #pragma unroll
;           for (int e = 0; e < 8; ++e) { const float f = bf2f((unsigned short)qr[d0][e]); q2 = fmaf(f, f, q2); }
;       q2 += sx(q2, 32, lane);
; #pragma unroll
;       for (int o_ = 1; o_ < 32; o_ <<= 1) q2 = fmaxf(q2, sx(q2, o_, lane));
;       if (lane == 0) li_l[0] = q2;
.LBB0_253:
	s_or_b64 exec, exec, s[0:1]
	s_waitcnt vmcnt(3)
	v_lshlrev_b32_e32 v2, 16, v140
	v_fma_f32 v2, v2, v2, 0
	v_and_b32_e32 v3, 0xffff0000, v140
	v_fmac_f32_e32 v2, v3, v3
	v_lshlrev_b32_e32 v3, 16, v141
	v_fmac_f32_e32 v2, v3, v3
	v_and_b32_e32 v3, 0xffff0000, v141
	v_fmac_f32_e32 v2, v3, v3
	v_lshlrev_b32_e32 v3, 16, v142
	v_fmac_f32_e32 v2, v3, v3
	v_and_b32_e32 v3, 0xffff0000, v142
	v_fmac_f32_e32 v2, v3, v3
	v_lshlrev_b32_e32 v3, 16, v143
	v_fmac_f32_e32 v2, v3, v3
	v_and_b32_e32 v3, 0xffff0000, v143
	v_fmac_f32_e32 v2, v3, v3
	s_waitcnt vmcnt(2)
	v_lshlrev_b32_e32 v3, 16, v136
	v_fmac_f32_e32 v2, v3, v3
	v_and_b32_e32 v3, 0xffff0000, v136
	v_fmac_f32_e32 v2, v3, v3
	v_lshlrev_b32_e32 v3, 16, v137
	v_fmac_f32_e32 v2, v3, v3
	v_and_b32_e32 v3, 0xffff0000, v137
	v_fmac_f32_e32 v2, v3, v3
	v_lshlrev_b32_e32 v3, 16, v138
	v_fmac_f32_e32 v2, v3, v3
	v_and_b32_e32 v3, 0xffff0000, v138
	v_fmac_f32_e32 v2, v3, v3
	v_lshlrev_b32_e32 v3, 16, v139
	v_fmac_f32_e32 v2, v3, v3
	v_and_b32_e32 v3, 0xffff0000, v139
	v_fmac_f32_e32 v2, v3, v3
	s_waitcnt vmcnt(1)
	v_lshlrev_b32_e32 v3, 16, v132
	v_fmac_f32_e32 v2, v3, v3
	v_and_b32_e32 v3, 0xffff0000, v132
	v_fmac_f32_e32 v2, v3, v3
	v_lshlrev_b32_e32 v3, 16, v133
	v_fmac_f32_e32 v2, v3, v3
	v_and_b32_e32 v3, 0xffff0000, v133
	v_fmac_f32_e32 v2, v3, v3
	v_lshlrev_b32_e32 v3, 16, v134
	v_fmac_f32_e32 v2, v3, v3
	v_and_b32_e32 v3, 0xffff0000, v134
	v_fmac_f32_e32 v2, v3, v3
	v_lshlrev_b32_e32 v3, 16, v135
	v_fmac_f32_e32 v2, v3, v3
	v_and_b32_e32 v3, 0xffff0000, v135
	v_fmac_f32_e32 v2, v3, v3
	s_waitcnt vmcnt(0)
	v_lshlrev_b32_e32 v3, 16, v128
	v_fmac_f32_e32 v2, v3, v3
	v_and_b32_e32 v3, 0xffff0000, v128
	v_fmac_f32_e32 v2, v3, v3
	v_lshlrev_b32_e32 v3, 16, v129
	v_fmac_f32_e32 v2, v3, v3
	v_and_b32_e32 v3, 0xffff0000, v129
	v_fmac_f32_e32 v2, v3, v3
	v_lshlrev_b32_e32 v3, 16, v130
	v_fmac_f32_e32 v2, v3, v3
	v_and_b32_e32 v3, 0xffff0000, v130
	v_fmac_f32_e32 v2, v3, v3
	v_lshlrev_b32_e32 v3, 16, v131
	v_and_b32_e32 v8, 63, v18
	v_fmac_f32_e32 v2, v3, v3
	v_and_b32_e32 v3, 0xffff0000, v131
	v_fmac_f32_e32 v2, v3, v3
	v_mov_b32_e32 v4, v2
	s_and_b32 s0, s3, 0x3fffffc0
	s_lshl_b32 s0, s0, 2
	s_add_i32 s30, s0, 0
	s_add_i32 s30, s30, 0x18000
	s_waitcnt lgkmcnt(0)
	v_permlane32_swap_b32_e32 v4, v2
	v_add_f32_e32 v2, v2, v4
	v_cmp_eq_u32_e32 vcc, 0, v8
	s_nop 1
	v_max_f32_dpp v2, v2, v2 quad_perm:[1,0,3,2] row_mask:0xf bank_mask:0xf
	s_nop 1
	v_max_f32_dpp v2, v2, v2 quad_perm:[2,3,0,1] row_mask:0xf bank_mask:0xf
	s_nop 1
	v_max_f32_dpp v2, v2, v2 row_half_mirror row_mask:0xf bank_mask:0xf
	s_nop 1
	v_max_f32_dpp v2, v2, v2 row_mirror row_mask:0xf bank_mask:0xf
	s_nop 1
	v_mov_b32_e32 v3, v2
	s_nop 1
	v_permlane16_swap_b32_e32 v3, v2
	s_and_saveexec_b64 s[0:1], vcc
	s_cbranch_execz .LBB0_255
	s_waitcnt lgkmcnt(0)
	v_max_f32_e32 v3, v3, v3
	v_max_f32_e32 v2, v2, v2
	v_max_f32_e32 v2, v2, v3
	v_mov_b32_e32 v3, s30
	ds_write_b32 v3, v2
